# norm1: the five per-condition vector loads issued together with one wait (was two serial round trips), on top of relu fusion
# speedup vs baseline: 1.0099x; 1.0001x over previous
.LBB0_1150:
	s_add_i32 s8, s6, 0xffffe000
	s_lshr_b32 s8, s8, 10
	s_add_i32 s8, s8, 1
	s_cmpk_gt_i32 s7, 0x3ff
	s_cselect_b32 s8, s8, 0
	v_mov_b64_e32 v[14:15], v[10:11]
	s_cmp_eq_u32 s8, s49
	v_mov_b64_e32 v[12:13], v[8:9]
	s_cbranch_scc1 .LBB0_1152
	v_mad_u64_u32 v[4:5], s[10:11], s8, v205, v[16:17]
	global_load_dwordx4 v[4:7], v[4:5], off
	s_nop 0
	global_load_dwordx4 v[8:11], v[18:19], off
	v_mad_u64_u32 v[52:53], s[10:11], s8, v205, v[20:21]
	s_mov_b32 s49, s8
	s_nop 0
	global_load_dwordx4 v[242:245], v[52:53], off
	global_load_dwordx4 v[12:15], v[22:23], off
	v_add_co_u32_e32 v52, vcc, 0x2000, v52
	s_nop 1
	v_addc_co_u32_e32 v53, vcc, 0, v53, vcc
	global_load_dwordx4 v[52:55], v[52:53], off
	s_waitcnt vmcnt(0)
	v_pk_mul_f32 v[8:9], v[4:5], v[8:9]
	v_pk_mul_f32 v[10:11], v[6:7], v[10:11]
	v_mov_b32_e32 v104, v52
	v_mov_b32_e32 v105, v54
	v_mov_b32_e32 v54, v53
	v_pk_add_f32 v[104:105], v[104:105], 1.0 op_sel_hi:[1,0]
	v_pk_add_f32 v[54:55], v[54:55], 1.0 op_sel_hi:[1,0]
	v_mov_b32_e32 v52, v12
	v_mov_b32_e32 v53, v14
	v_mov_b32_e32 v14, v13
	v_pk_mul_f32 v[52:53], v[52:53], v[104:105]
	v_pk_mul_f32 v[54:55], v[14:15], v[54:55]
	v_mov_b64_e32 v[4:5], v[242:243]
	v_mov_b64_e32 v[6:7], v[244:245]
	v_mov_b64_e32 v[12:13], v[8:9]
	v_mov_b64_e32 v[14:15], v[10:11]
